# FoX attn: unmasked-tile path hand-scheduled (bias row loaded straight into score accumulators, exp in MFMA gaps), wave-0 gate scan via DPP
# speedup vs baseline: 1.0353x; 1.0164x over previous
; #define LAS __attribute__((address_space(3)))
; #define ATT_LOAD(jt) do { ATT_LOADK(jt); ATT_LOADV(jt); } while (0)
; template <int MODE>
; __device__ __forceinline__ void attn_item(const AttnP& p, int b, int h, int qb, LAS unsigned char* lds) {
;     ...
;         float sc = 0.125f * LOG2E;
;         if (MODE != 1) { ss += __shfl_xor(ss, 32); sc *= 1.0f / sqrtf(ss * (1.0f / 64.0f) + 1e-6f); }
; #pragma unroll
;         for (int ks = 0; ks < 4; ++ks) {
;             u32x4 o;
; #pragma unroll
;             for (int e = 0; e < 4; ++e) {
;                 float lo = bflo(raw[ks][e]) * sc, hi = bfhi(raw[ks][e]) * sc;
;                 if (MODE != 1) {
;                     const int d = ks * 16 + hh * 8 + 2 * e;
;                     const float* gq = p.qk_gain + ((MODE == 0) ? 0 : 128); const float* gk = gq + 64;
;                     lo *= gq[d] * gk[d]; hi *= gq[d + 1] * gk[d + 1];
;                 }
;                 o[e] = pk2(lo, hi);
;             }
;             Qf[c][ks] = __builtin_bit_cast(bf16x8, o);
;             if (QPARK) *(LAS u32x4*)(lds + QP_OFF + w * 8192 + ((c * 4 + ks) * 64 + lane) * 16) = o;
;         }
;     }
;     if (MODE == 0) { LAS float* tab = (LAS float*)(lds + TAB_OFF); if (tid < 256) tab[tid] = p.biasT[h * 256 + tid]; }
;     LAS unsigned* flags = (LAS unsigned*)(lds + FLAG_OFF);
;     if (MODE == 1 && tid < 16) flags[tid] = 0u;
;     f32x16 O[NC][DV / 32];
; #pragma unroll
;     for (int c = 0; c < NC; ++c)
; #pragma unroll
;         for (int d = 0; d < DV / 32; ++d)
; #pragma unroll
;             for (int i = 0; i < 16; ++i) O[c][d][i] = 0.f;
;     float mrun[NC], lsum[NC];
; #pragma unroll
;     for (int c = 0; c < NC; ++c) { mrun[c] = -1e30f; lsum[c] = 0.f; }
;     float R2 = 0.f; bool mydone = false;
;     float carry = 0.f, bq0 = 0.f, qk2 = 0.f;
;     LAS unsigned* cflags = flags + 32;
;     if (MODE == 2) {
;         if (tid < 4) cflags[tid] = 0u;
;         float gq_ = fabsf(p.qk_gain[128 + lane]), gk_ = fabsf(p.qk_gain[192 + lane]);
; #pragma unroll
;         for (int o_ = 1; o_ < 64; o_ <<= 1) { gq_ = fmaxf(gq_, __shfl_xor(gq_, o_)); gk_ = fmaxf(gk_, __shfl_xor(gk_, o_)); }
;         qk2 = 8.0f * gq_ * gk_ * LOG2E * 1.02f;
;     }
;     const float fb = (MODE == 2) ? p.fbias[h] : 0.f;
;     ...
;     ATT_LOAD(jt_max);
;     ATT_STORE(0, jt_max);
;     __syncthreads();
;     float mfix = 0.f;
;     if (MODE == 2) mfix = qk2;
.LBB0_225:
	v_pk_mul_f32 v[12:13], v[12:13], v[16:17]
	v_add_f32_e32 v16, v125, v126
	v_fmamk_f32 v16, v16, 0x3c800000, v211
	v_mul_f32_e32 v17, 0x4f800000, v16
	v_cmp_gt_f32_e32 vcc, s55, v16
	v_pk_mul_f32 v[2:3], v[2:3], v[6:7]
	v_pk_mul_f32 v[6:7], v[28:29], v[36:37]
	v_pk_mul_f32 v[28:29], v[40:41], v[48:49]
	v_cndmask_b32_e32 v40, v16, v17, vcc
	v_sqrt_f32_e32 v41, v40
	v_pk_mul_f32 v[30:31], v[30:31], v[42:43]
	v_pk_mul_f32 v[18:19], v[18:19], v[22:23]
	v_pk_mul_f32 v[20:21], v[20:21], v[24:25]
	v_add_u32_e32 v42, -1, v41
	v_fma_f32 v43, -v42, v41, v40
	v_cmp_ge_f32_e64 s[0:1], 0, v43
	v_add_u32_e32 v43, 1, v41
	v_pk_mul_f32 v[26:27], v[26:27], v[34:35]
	v_cndmask_b32_e64 v42, v41, v42, s[0:1]
	v_fma_f32 v41, -v43, v41, v40
	v_cmp_lt_f32_e64 s[0:1], 0, v41
	v_pk_mul_f32 v[34:35], v[38:39], v[46:47]
	v_pk_mul_f32 v[38:39], v[58:59], v[72:73]
	v_cndmask_b32_e64 v41, v42, v43, s[0:1]
	v_mul_f32_e32 v42, 0x37800000, v41
	v_cndmask_b32_e32 v41, v41, v42, vcc
	v_cmp_class_f32_e32 vcc, v40, v212
	v_pk_mul_f32 v[16:17], v[50:51], v[54:55]
	v_pk_mul_f32 v[36:37], v[60:61], v[74:75]
	v_cndmask_b32_e32 v40, v41, v40, vcc
	v_div_scale_f32 v41, s[0:1], v40, v40, 1.0
	v_rcp_f32_e32 v42, v41
	v_pk_mul_f32 v[10:11], v[10:11], v[14:15]
	v_pk_mul_f32 v[14:15], v[52:53], v[56:57]
	v_max_f32_e32 v93, v93, v93
	v_fma_f32 v22, -v41, v42, 1.0
	v_fmac_f32_e32 v42, v22, v42
	v_div_scale_f32 v22, vcc, 1.0, v40, 1.0
	v_mul_f32_e32 v23, v22, v42
	v_fma_f32 v24, -v41, v23, v22
	v_fmac_f32_e32 v23, v24, v42
	v_fma_f32 v22, -v41, v23, v22
	v_div_fmas_f32 v22, v22, v42, v23
	v_div_fixup_f32 v22, v22, v40, 1.0
	v_mul_f32_e32 v22, 0x3e38aa3b, v22
	v_pk_mul_f32 v[24:25], v[22:23], v[106:107] op_sel_hi:[0,1]
	v_pk_mul_f32 v[18:19], v[18:19], v[24:25]
	v_max_f32_e32 v91, v91, v91
	v_cvt_pk_bf16_f32 v72, v18, v19
	v_pk_mul_f32 v[18:19], v[22:23], v[104:105] op_sel_hi:[0,1]
	v_pk_mul_f32 v[18:19], v[20:21], v[18:19]
	v_pk_mul_f32 v[32:33], v[32:33], v[44:45]
	v_cvt_pk_bf16_f32 v73, v18, v19
	v_pk_mul_f32 v[18:19], v[22:23], v[102:103] op_sel_hi:[0,1]
	v_pk_mul_f32 v[16:17], v[16:17], v[18:19]
	v_max_f32_e32 v91, v91, v93
	v_cvt_pk_bf16_f32 v74, v16, v17
	v_pk_mul_f32 v[16:17], v[22:23], v[100:101] op_sel_hi:[0,1]
	v_pk_mul_f32 v[14:15], v[14:15], v[16:17]
	v_mov_b32_e32 v93, v83
	v_cvt_pk_bf16_f32 v75, v14, v15
	v_pk_mul_f32 v[14:15], v[22:23], v[76:77] op_sel_hi:[0,1]
	v_pk_mul_f32 v[10:11], v[10:11], v[14:15]
	v_mov_b32_e32 v83, v109
	v_cvt_pk_bf16_f32 v76, v10, v11
	v_pk_mul_f32 v[10:11], v[22:23], v[98:99] op_sel_hi:[0,1]
	v_pk_mul_f32 v[10:11], v[10:11], v[12:13]
	v_max_f32_e32 v121, v121, v121
	v_cvt_pk_bf16_f32 v77, v10, v11
	v_pk_mul_f32 v[10:11], v[22:23], v[78:79] op_sel_hi:[0,1]
	v_pk_mul_f32 v[10:11], v[10:11], v[38:39]
	v_max_f32_e32 v63, v63, v63
	v_cvt_pk_bf16_f32 v78, v10, v11
	v_pk_mul_f32 v[10:11], v[22:23], v[96:97] op_sel_hi:[0,1]
	v_pk_mul_f32 v[10:11], v[10:11], v[36:37]
	v_max_f32_e32 v63, v63, v121
	v_cvt_pk_bf16_f32 v79, v10, v11
	v_pk_mul_f32 v[10:11], v[22:23], v[80:81] op_sel_hi:[0,1]
	v_pk_mul_f32 v[10:11], v[10:11], v[30:31]
	v_mul_f32_e32 v63, 0x41000000, v63
	v_cvt_pk_bf16_f32 v80, v10, v11
	v_pk_mul_f32 v[10:11], v[22:23], v[94:95] op_sel_hi:[0,1]
	v_pk_mul_f32 v[10:11], v[10:11], v[32:33]
	v_mul_f32_e32 v63, v91, v63
	v_cvt_pk_bf16_f32 v81, v10, v11
	v_pk_mul_f32 v[10:11], v[22:23], v[82:83] op_sel_hi:[0,1]
	v_pk_mul_f32 v[10:11], v[10:11], v[34:35]
	v_mov_b32_e32 v91, v85
	v_cvt_pk_bf16_f32 v82, v10, v11
	v_pk_mul_f32 v[10:11], v[22:23], v[92:93] op_sel_hi:[0,1]
	v_mov_b32_e32 v85, v111
	v_pk_mul_f32 v[10:11], v[10:11], v[28:29]
	v_mul_f32_e32 v63, 0x3fb8aa3b, v63
	v_cvt_pk_bf16_f32 v83, v10, v11
	v_pk_mul_f32 v[10:11], v[22:23], v[84:85] op_sel_hi:[0,1]
	v_pk_mul_f32 v[10:11], v[10:11], v[26:27]
	v_mul_f32_e32 v121, 0x3f828f5c, v63
	v_cvt_pk_bf16_f32 v84, v10, v11
	v_pk_mul_f32 v[10:11], v[22:23], v[90:91] op_sel_hi:[0,1]
	v_mov_b32_e32 v63, v87
	v_mov_b32_e32 v87, v113
	v_pk_mul_f32 v[6:7], v[10:11], v[6:7]
	v_pk_mul_f32 v[4:5], v[4:5], v[8:9]
	v_cvt_pk_bf16_f32 v85, v6, v7
	v_pk_mul_f32 v[6:7], v[22:23], v[86:87] op_sel_hi:[0,1]
	v_pk_mul_f32 v[2:3], v[6:7], v[2:3]
	v_lshlrev_b32_e32 v94, 2, v124
	v_cvt_pk_bf16_f32 v86, v2, v3
	v_pk_mul_f32 v[2:3], v[22:23], v[62:63] op_sel_hi:[0,1]
	v_pk_mul_f32 v[2:3], v[2:3], v[4:5]
	v_cmp_ne_u32_e32 vcc, 63, v130
	v_cvt_pk_bf16_f32 v87, v2, v3
	v_lshl_add_u64 v[2:3], s[68:69], 0, v[0:1]
	v_lshrrev_b32_e32 v0, 2, v123
	v_lshl_add_u64 v[90:91], v[2:3], 0, s[92:93]
	v_and_or_b32 v0, v0, 3, v94
	v_lshlrev_b32_e32 v3, 2, v123
	v_and_b32_e32 v2, 16, v123
	v_and_b32_e32 v3, 12, v3
	v_mul_u32_u24_e32 v0, 0x60, v0
	v_or3_b32 v0, v3, v2, v0
	v_lshlrev_b32_e32 v97, 1, v0
	v_addc_co_u32_e32 v0, vcc, 0, v216, vcc
	v_cmp_gt_u32_e32 vcc, 62, v130
	v_lshlrev_b32_e32 v101, 2, v0
	s_or_b32 s31, s27, 31
	v_cndmask_b32_e64 v0, 0, 2, vcc
	v_cmp_gt_u32_e32 vcc, 60, v130
	v_add_lshl_u32 v102, v0, v216, 2
	s_add_u32 s18, s84, s18
	v_cndmask_b32_e64 v0, 0, 4, vcc
	v_cmp_gt_u32_e32 vcc, 56, v130
	v_add_lshl_u32 v103, v0, v216, 2
	s_addc_u32 s19, s85, 0
	v_cndmask_b32_e64 v0, 0, 8, vcc
	v_cmp_gt_u32_e32 vcc, 48, v130
	v_add_lshl_u32 v104, v0, v216, 2
	s_add_i32 s15, s26, 0xf80
	v_cndmask_b32_e64 v0, 0, 16, vcc
	v_add_lshl_u32 v105, v0, v216, 2
	s_lshl_b32 s14, s22, 8
	v_add_u32_e32 v0, s15, v89
	s_sub_i32 s33, 0xfff, s14
	v_subrev_u32_e32 v0, s14, v0
	s_movk_i32 s14, 0x140
	v_mov_b32_e32 v14, v1
	v_mov_b32_e32 v15, v1
	v_mul_lo_u32 v92, v0, s14
	v_mov_b32_e32 v0, v1
	v_mov_b32_e32 v2, v1
	v_mov_b32_e32 v3, v1
	v_mov_b32_e32 v4, v1
	v_mov_b32_e32 v5, v1
	v_mov_b32_e32 v6, v1
	v_mov_b32_e32 v7, v1
	v_mov_b32_e32 v8, v1
	v_mov_b32_e32 v9, v1
	v_mov_b32_e32 v10, v1
	v_mov_b32_e32 v11, v1
	v_mov_b32_e32 v12, v1
	v_mov_b32_e32 v13, v1
	v_mov_b64_e32 v[30:31], v[14:15]
	v_mov_b64_e32 v[46:47], v[14:15]
	s_mov_b32 s30, 0
	v_cmp_eq_u32_e64 s[0:1], 0, v89
	v_fmaak_f32 v95, 2.0, v121, 0x41400000
	v_mul_u32_u24_e32 v96, 0x90, v122
	v_or_b32_e32 v98, 0x1800, v97
	v_add_u32_e32 v99, 0x2400, v97
	v_add_u32_e32 v100, 0xc00, v97
	v_cmp_eq_u32_e64 s[16:17], 63, v89
	v_cmp_gt_u32_e64 s[4:5], 62, v89
	v_cmp_gt_u32_e64 s[6:7], 60, v89
	v_cmp_gt_u32_e64 s[8:9], 56, v89
	v_cmp_gt_u32_e64 s[10:11], 48, v89
	v_cmp_gt_u32_e64 s[12:13], 32, v89
	v_add_u32_e32 v106, s26, v127
	s_mov_b32 s34, s29
	v_mov_b64_e32 v[28:29], v[12:13]
	v_mov_b64_e32 v[26:27], v[10:11]
	v_mov_b64_e32 v[24:25], v[8:9]
	v_mov_b64_e32 v[22:23], v[6:7]
	v_mov_b64_e32 v[20:21], v[4:5]
	v_mov_b64_e32 v[18:19], v[2:3]
	v_mov_b64_e32 v[16:17], v[0:1]
	v_mov_b64_e32 v[44:45], v[12:13]
	v_mov_b64_e32 v[42:43], v[10:11]
	v_mov_b64_e32 v[40:41], v[8:9]
	v_mov_b64_e32 v[38:39], v[6:7]
	v_mov_b64_e32 v[36:37], v[4:5]
	v_mov_b64_e32 v[34:35], v[2:3]
	v_mov_b64_e32 v[32:33], v[0:1]
	v_mov_b32_e32 v0, 0
	s_waitcnt lgkmcnt(0)
	s_barrier
	v_mov_b32_e32 v121, 0
	s_branch .LBB0_228

; template <int MODE>
; __device__ __forceinline__ void attn_item(const AttnP& p, int b, int h, int qb, LAS unsigned char* lds) {
;     ...
;             const int kp0 = k0 + 32 * kb2;
;             bool active = (MODE == 1) ? (kp0 <= qw + 30) : (kp0 <= qw + 31);
;             if (MODE == 1) active = active && !mydone;
;             if (active) {
;                 f32x16 S[NC];
;     ...
;                 if (MODE == 1) ATT_QK(0, 0.f);
;                 const bool need_mask = (MODE == 1) ? (kp0 + 31 >= qw) : (kp0 + 31 > qw);
.LBB0_232:
	s_and_b32 s35, s30, 1
	s_mul_i32 s24, s35, 0x5500
	s_add_i32 s36, s24, 0
	v_add_u32_e32 v2, s36, v88
	s_sub_i32 s24, s33, 31
	v_lshl_add_u32 v8, v94, 2, s36
	s_cmp_le_i32 s33, s27
	s_cbranch_scc1 .Lfox_far
	s_cmp_gt_i32 s24, s31
	v_add_u32_e32 v6, v2, v96
	v_add_u32_e32 v7, s33, v94
	s_cbranch_scc0 .LBB0_235
	s_sub_i32 s24, s33, 63
	s_cmp_gt_i32 s24, s31
	s_cbranch_scc0 .LBB0_236

.LBB0_237:
	s_waitcnt vmcnt(0) lgkmcnt(0)
	v_and_b32_e32 v7, 0xffff0000, v67
	v_and_b32_e32 v5, 0xffff0000, v66
	v_lshlrev_b32_e32 v6, 16, v67
	v_lshlrev_b32_e32 v4, 16, v66
	v_mov_b32_e32 v8, v7
	v_mov_b32_e32 v9, v5
	v_mov_b32_e32 v2, v6
	v_mov_b32_e32 v3, v4
	v_pk_mul_f32 v[8:9], v[8:9], v[8:9]
	v_and_b32_e32 v11, 0xffff0000, v64
	v_pk_fma_f32 v[2:3], v[2:3], v[2:3], v[8:9]
	v_and_b32_e32 v9, 0xffff0000, v65
	v_lshlrev_b32_e32 v8, 16, v65
	v_lshlrev_b32_e32 v10, 16, v64
	v_mov_b32_e32 v14, v11
	v_mov_b32_e32 v15, v9
	v_mov_b32_e32 v12, v10
	v_mov_b32_e32 v13, v8
	v_pk_mul_f32 v[14:15], v[14:15], v[14:15]
	s_xor_b32 s22, s35, 1
	v_pk_fma_f32 v[12:13], v[12:13], v[12:13], v[14:15]
	s_mulk_i32 s22, 0x5500
	v_add_f32_e32 v12, v12, v13
	v_add_f32_e32 v3, v3, v12
	v_add_f32_e32 v2, v2, v3
	s_add_i32 s22, s22, 0
	v_add_u32_e32 v13, s22, v108
	v_add_f32_dpp v2, v2, v2 quad_perm:[1,0,3,2] row_mask:0xf bank_mask:0xf bound_ctrl:1
	s_and_b64 vcc, exec, s[14:15]
	s_nop 0
	v_add_f32_dpp v2, v2, v2 quad_perm:[2,3,0,1] row_mask:0xf bank_mask:0xf bound_ctrl:1
	s_nop 1
	v_add_f32_dpp v2, v2, v2 row_half_mirror row_mask:0xf bank_mask:0xf bound_ctrl:1
	v_fmamk_f32 v2, v2, 0x3c800000, v211
	v_rsq_f32_e32 v12, v2
	s_nop 0
	v_pk_mul_f32 v[2:3], v[12:13], v[10:11] op_sel_hi:[0,1]
	v_pk_mul_f32 v[8:9], v[12:13], v[8:9] op_sel_hi:[0,1]
	v_pk_mul_f32 v[4:5], v[12:13], v[4:5] op_sel_hi:[0,1]
	v_pk_mul_f32 v[6:7], v[12:13], v[6:7] op_sel_hi:[0,1]
	v_cvt_pk_bf16_f32 v2, v2, v3
	v_cvt_pk_bf16_f32 v3, v8, v9
	v_cvt_pk_bf16_f32 v4, v4, v5
	v_cvt_pk_bf16_f32 v5, v6, v7
	v_add_u32_e32 v6, s22, v116
	ds_write_b128 v13, v[2:5]
	ds_write_b128 v6, v[68:71] offset:9216
	s_cbranch_vccnz .LBB0_227
	v_add_f32_e32 v2, v110, v112
	v_mul_f32_e64 v3, |v2|, s40
	v_exp_f32_e32 v3, v3
	v_min_f32_e32 v2, 0, v2
	s_cmp_lg_u32 s30, 2
	v_add_f32_e32 v3, 1.0, v3
	v_cmp_gt_f32_e32 vcc, s78, v3
	s_nop 1
	v_cndmask_b32_e64 v4, 0, 32, vcc
	v_ldexp_f32 v3, v3, v4
	v_log_f32_e32 v3, v3
	v_cndmask_b32_e32 v4, 0, v218, vcc
	v_mul_f32_e32 v5, 0x3f317217, v3
	v_fma_f32 v5, v3, s79, -v5
	v_fmac_f32_e32 v5, 0x3377d1cf, v3
	v_fmac_f32_e32 v5, 0x3f317217, v3
	v_cmp_lt_f32_e64 vcc, |v3|, s37
	s_nop 1
	v_cndmask_b32_e32 v3, v3, v5, vcc
	v_sub_f32_e32 v3, v3, v4
	v_sub_f32_e32 v2, v2, v3
	v_mov_b32_e32 v3, v2
	s_nop 1
	v_add_f32_dpp v3, v3, v3 row_shl:1 row_mask:0xf bank_mask:0xf bound_ctrl:1
	s_nop 1
	v_add_f32_dpp v3, v3, v3 row_shl:2 row_mask:0xf bank_mask:0xf bound_ctrl:1
	s_nop 1
	v_add_f32_dpp v3, v3, v3 row_shl:4 row_mask:0xf bank_mask:0xf bound_ctrl:1
	s_nop 1
	v_add_f32_dpp v3, v3, v3 row_shl:8 row_mask:0xf bank_mask:0xf bound_ctrl:1
	s_nop 1
	v_readlane_b32 s23, v3, 48
	v_readlane_b32 s24, v3, 32
	v_readlane_b32 s25, v3, 16
	s_nop 1
	v_mov_b32_e32 v4, s23
	v_mov_b32_e32 v5, s24
	v_mov_b32_e32 v6, s25
	s_nop 1
	v_add_f32_dpp v3, v4, v3 quad_perm:[0,1,2,3] row_mask:0x7 bank_mask:0xf
	s_nop 1
	v_add_f32_dpp v3, v5, v3 quad_perm:[0,1,2,3] row_mask:0x3 bank_mask:0xf
	s_nop 1
	v_add_f32_dpp v3, v6, v3 quad_perm:[0,1,2,3] row_mask:0x1 bank_mask:0xf
	v_sub_f32_e32 v4, v3, v2
	v_readlane_b32 s23, v3, 0
	v_add_f32_e32 v3, v120, v4
	v_mul_f32_e32 v3, 0x3fb8aa3b, v3
	v_lshl_add_u32 v4, v89, 2, s22
	ds_write_b32 v4, v3 offset:21504
	s_cbranch_scc1 .LBB0_240
	v_readlane_b32 s24, v3, 0
	s_nop 1
	v_mov_b32_e32 v117, s24
.LBB0_240:
	v_add_f32_e32 v120, s23, v120
	s_and_saveexec_b64 s[14:15], s[0:1]
	s_cbranch_execz .LBB0_226
	s_add_i32 s22, s34, -1
	s_and_b32 s23, s22, 3
	s_lshl_b32 s23, s23, 2
	s_add_i32 s24, s23, 0
	v_fmamk_f32 v2, v120, 0x3fb8aa3b, v95
	s_cmp_le_i32 s22, s28
	s_waitcnt lgkmcnt(0)
	v_sub_f32_e32 v2, v2, v117
	s_mov_b32 s25, 0xc2000000
	s_cselect_b64 s[22:23], -1, 0
	v_cmp_gt_f32_e32 vcc, s25, v2
	s_and_b64 s[22:23], s[22:23], vcc
	v_cndmask_b32_e64 v2, 0, 1, s[22:23]
	v_mov_b32_e32 v3, s24
	ds_write_b32 v3, v2 offset:44672
	s_branch .LBB0_226
; #define LAS __attribute__((address_space(3)))
; #define MFMA32(a, b, c) __builtin_amdgcn_mfma_f32_32x32x16_bf16((a), (b), (c), 0, 0, 0)
; __device__ __forceinline__ s16x4 vtr(const LAS unsigned char* p) { return __builtin_bit_cast(s16x4, __builtin_amdgcn_ds_read_tr16_b64_v4i16((LAS v4i16_t*)p)); }
; __device__ __forceinline__ int crow(int r, int hi) { return (r & 3) + 8 * (r >> 2) + 4 * hi; }
; template <int MODE>
; __device__ __forceinline__ void attn_item(const AttnP& p, int b, int h, int qb, LAS unsigned char* lds) {
;     ...
;                     } else {
;                         float binit[16];
;                         const LAS float* bl = (const LAS float*)(vtb + VT_BYTES) + 32 * kb2 + 4 * hh;
; #pragma unroll
;                         for (int g = 0; g < 4; ++g) {
;                             const f32x4 t = *(const LAS f32x4*)(bl + 8 * g);
; #pragma unroll
;                             for (int e = 0; e < 4; ++e) binit[4 * g + e] = (need_mask && (kp0 + crow(4 * g + e, hh) > qrow)) ? -3e38f : (t[e] - mfix);
;                         }
;                         ATT_QK(0, binit[i]); ATT_TAIL(0);
;                     }
;     ...
;                 }
; #pragma unroll
;                 for (int t2 = 0; t2 < 2; ++t2)
; #pragma unroll
;                     for (int d = 0; d < DV / 32; ++d) {
;                         const LAS unsigned char* vp = vtb + ((32 * kb2 + 16 * t2 + 4 * hh + ((lane & 15) >> 2)) * VPT + d * 32 + 16 * ((lane >> 4) & 1) + 4 * (lane & 3)) * 2;
;                         const s16x4 lo = vtr(vp), hi = vtr(vp + 8 * VPT * 2);
;                         const bf16x8 va = __builtin_shufflevector(lo, hi, 0, 1, 2, 3, 4, 5, 6, 7);
; #pragma unroll
;                         for (int c = 0; c < NC; ++c) O[c][d] = MFMA32(va, pb[c][t2], O[c][d]);
;                     }
.Lfox_far:
	v_add_u32_e32 v6, v2, v96
	v_add_u32_e32 v193, s36, v98
	v_add_u32_e32 v221, s36, v99
	v_add_u32_e32 v246, s36, v97
	v_add_u32_e32 v247, s36, v100
	ds_read_b128 v[140:143], v8 offset:21632
	ds_read_b128 v[144:147], v8 offset:21664
	ds_read_b128 v[148:151], v8 offset:21696
	ds_read_b128 v[152:155], v8 offset:21728
	ds_read_b128 v[172:175], v6 offset:4608
	ds_read_b128 v[176:179], v6 offset:4640
	ds_read_b128 v[180:183], v6 offset:4672
	ds_read_b128 v[184:187], v6 offset:4704
	ds_read_b128 v[156:159], v8 offset:21504
	ds_read_b128 v[160:163], v8 offset:21536
	ds_read_b128 v[164:167], v8 offset:21568
	ds_read_b128 v[168:171], v8 offset:21600
	s_waitcnt lgkmcnt(7)
	v_mfma_f32_32x32x16_bf16 v[140:155], v[172:175], v[72:75], v[140:155]
	ds_read_b128 v[222:225], v6 offset:0
	s_waitcnt lgkmcnt(7)
	v_mfma_f32_32x32x16_bf16 v[140:155], v[176:179], v[76:79], v[140:155]
	ds_read_b128 v[226:229], v6 offset:32
	s_waitcnt lgkmcnt(7)
	v_mfma_f32_32x32x16_bf16 v[140:155], v[180:183], v[80:83], v[140:155]
	ds_read_b128 v[230:233], v6 offset:64
	s_waitcnt lgkmcnt(7)
	v_mfma_f32_32x32x16_bf16 v[140:155], v[184:187], v[84:87], v[140:155]
	ds_read_b128 v[234:237], v6 offset:96
	ds_read_b64_tr_b16 v[188:189], v193 offset:9216
	ds_read_b64_tr_b16 v[190:191], v193 offset:10752
	ds_read_b64_tr_b16 v[206:207], v193 offset:9280
	ds_read_b64_tr_b16 v[208:209], v193 offset:10816
	s_waitcnt lgkmcnt(7)
	v_mfma_f32_32x32x16_bf16 v[156:171], v[222:225], v[72:75], v[156:171]
	ds_read_b64_tr_b16 v[238:239], v221 offset:9216
	ds_read_b64_tr_b16 v[240:241], v221 offset:10752
	ds_read_b64_tr_b16 v[242:243], v221 offset:9280
	ds_read_b64_tr_b16 v[244:245], v221 offset:10816
	s_nop 1
	v_exp_f32_e32 v140, v140
	v_exp_f32_e32 v141, v141
	v_exp_f32_e32 v142, v142
	v_add_f32_e32 v192, v140, v141
	v_exp_f32_e32 v143, v143
	v_add_f32_e32 v192, v142, v192
	v_exp_f32_e32 v144, v144
	v_add_f32_e32 v192, v143, v192
	v_exp_f32_e32 v145, v145
	v_add_f32_e32 v192, v144, v192
	s_waitcnt lgkmcnt(10)
	v_mfma_f32_32x32x16_bf16 v[156:171], v[226:229], v[76:79], v[156:171]
	ds_read_b64_tr_b16 v[180:181], v246 offset:9216
	ds_read_b64_tr_b16 v[182:183], v246 offset:10752
	ds_read_b64_tr_b16 v[184:185], v246 offset:9280
	ds_read_b64_tr_b16 v[186:187], v246 offset:10816
	v_exp_f32_e32 v146, v146
	v_add_f32_e32 v192, v145, v192
	v_exp_f32_e32 v147, v147
	v_add_f32_e32 v192, v146, v192
	v_cvt_pk_bf16_f32 v140, v140, v141
	v_add_f32_e32 v192, v147, v192
	v_cvt_pk_bf16_f32 v141, v142, v143
	v_cvt_pk_bf16_f32 v142, v144, v145
	v_cvt_pk_bf16_f32 v143, v146, v147
	v_exp_f32_e32 v148, v148
	s_waitcnt lgkmcnt(13)
	v_mfma_f32_32x32x16_bf16 v[156:171], v[230:233], v[80:83], v[156:171]
	v_exp_f32_e32 v149, v149
	v_add_f32_e32 v192, v148, v192
	v_exp_f32_e32 v150, v150
	v_add_f32_e32 v192, v149, v192
	v_exp_f32_e32 v151, v151
	v_add_f32_e32 v192, v150, v192
	v_exp_f32_e32 v152, v152
	v_add_f32_e32 v192, v151, v192
	v_exp_f32_e32 v153, v153
	v_add_f32_e32 v192, v152, v192
	s_waitcnt lgkmcnt(12)
	v_mfma_f32_32x32x16_bf16 v[156:171], v[234:237], v[84:87], v[156:171]
	v_exp_f32_e32 v154, v154
	v_add_f32_e32 v192, v153, v192
	v_exp_f32_e32 v155, v155
	v_add_f32_e32 v192, v154, v192
	v_cvt_pk_bf16_f32 v144, v148, v149
	v_add_f32_e32 v192, v155, v192
	v_cvt_pk_bf16_f32 v145, v150, v151
	v_cvt_pk_bf16_f32 v146, v152, v153
	v_cvt_pk_bf16_f32 v147, v154, v155
	v_add_f32_e32 v0, v0, v192
	s_waitcnt lgkmcnt(8)
	ds_read_b64_tr_b16 v[172:173], v247 offset:9216
	ds_read_b64_tr_b16 v[174:175], v247 offset:10752
	ds_read_b64_tr_b16 v[176:177], v247 offset:9280
	ds_read_b64_tr_b16 v[178:179], v247 offset:10816
	v_mfma_f32_32x32x16_bf16 v[32:47], v[188:191], v[140:143], v[32:47]
	v_exp_f32_e32 v156, v156
	v_exp_f32_e32 v157, v157
	v_exp_f32_e32 v158, v158
	v_add_f32_e32 v192, v156, v157
	v_exp_f32_e32 v159, v159
	v_add_f32_e32 v192, v158, v192
	v_exp_f32_e32 v160, v160
	v_add_f32_e32 v192, v159, v192
	v_exp_f32_e32 v161, v161
	v_add_f32_e32 v192, v160, v192
	v_mfma_f32_32x32x16_bf16 v[16:31], v[206:209], v[140:143], v[16:31]
	v_exp_f32_e32 v162, v162
	v_add_f32_e32 v192, v161, v192
	v_exp_f32_e32 v163, v163
	v_add_f32_e32 v192, v162, v192
	v_cvt_pk_bf16_f32 v156, v156, v157
	v_add_f32_e32 v192, v163, v192
	v_cvt_pk_bf16_f32 v157, v158, v159
	v_cvt_pk_bf16_f32 v158, v160, v161
	v_cvt_pk_bf16_f32 v159, v162, v163
	v_exp_f32_e32 v164, v164
	s_waitcnt lgkmcnt(10)
	v_mfma_f32_32x32x16_bf16 v[32:47], v[238:241], v[144:147], v[32:47]
	v_exp_f32_e32 v165, v165
	v_add_f32_e32 v192, v164, v192
	v_exp_f32_e32 v166, v166
	v_add_f32_e32 v192, v165, v192
	v_exp_f32_e32 v167, v167
	v_add_f32_e32 v192, v166, v192
	v_exp_f32_e32 v168, v168
	v_add_f32_e32 v192, v167, v192
	v_exp_f32_e32 v169, v169
	v_add_f32_e32 v192, v168, v192
	s_waitcnt lgkmcnt(8)
	v_mfma_f32_32x32x16_bf16 v[16:31], v[242:245], v[144:147], v[16:31]
	v_exp_f32_e32 v170, v170
	v_add_f32_e32 v192, v169, v192
	v_exp_f32_e32 v171, v171
	v_add_f32_e32 v192, v170, v192
	v_cvt_pk_bf16_f32 v160, v164, v165
	v_add_f32_e32 v192, v171, v192
	v_cvt_pk_bf16_f32 v161, v166, v167
	v_cvt_pk_bf16_f32 v162, v168, v169
	v_cvt_pk_bf16_f32 v163, v170, v171
	v_add_f32_e32 v0, v0, v192
	s_nop 1
	s_waitcnt lgkmcnt(6)
	v_mfma_f32_32x32x16_bf16 v[32:47], v[180:183], v[156:159], v[32:47]
	s_waitcnt lgkmcnt(4)
	v_mfma_f32_32x32x16_bf16 v[16:31], v[184:187], v[156:159], v[16:31]
	s_waitcnt lgkmcnt(2)
	v_mfma_f32_32x32x16_bf16 v[32:47], v[172:175], v[160:163], v[32:47]
	s_waitcnt lgkmcnt(0)
	v_mfma_f32_32x32x16_bf16 v[16:31], v[176:179], v[160:163], v[16:31]
	s_branch .LBB0_234
